# GLA chain phase A: LDS read waits moved to each MFMA's first consumer (counted lgkmcnt) instead of one full wait before the first MFMA
# baseline (speedup 1.0000x reference)
; __device__ __forceinline__ void gla_prompt_unit(const Ctx& P, int l, int b, int h, int eh, LAS unsigned char* lds) {
;     ...
;         { bf16x8 ka[2][4], qv[2][4];
; #pragma unroll
;           for (int ii = 0; ii < 2; ++ii) { const int idx = 2 * w + ii, si = idx >> 2, ti = idx & 3;
; #pragma unroll
;               for (int ks = 0; ks < 4; ++ks) { const int sw = ((ks * 4 + fq) ^ fr) * 16; ka[ii][ks] = *(const LAS bf16x8*)(kb + (16 * si + fr) * QS + sw); qv[ii][ks] = *(const LAS bf16x8*)(qb + (16 * ti + fr) * QS + sw); } }
;           __builtin_amdgcn_sched_barrier(0);
;           f32x4 acc[2];
; #pragma unroll
;           for (int ii = 0; ii < 2; ++ii) acc[ii] = (f32x4){0.f, 0.f, 0.f, 0.f};
; #pragma unroll
;           for (int ks = 0; ks < 4; ++ks)
; #pragma unroll
;               for (int ii = 0; ii < 2; ++ii) acc[ii] = MFMA16(ka[ii][ks], qv[ii][ks], acc[ii]);
; #pragma unroll
;           for (int ii = 0; ii < 2; ++ii) { const int idx = 2 * w + ii, si = idx >> 2, ti = idx & 3;
;               const int t = 16 * ti + fr;
;               float a0 = acc[ii][0], a1 = acc[ii][1], a2 = acc[ii][2], a3 = acc[ii][3]; const int s0 = 16 * si + fq * 4;
;               if (s0 + 0 > t) a0 = 0.f; if (s0 + 1 > t) a1 = 0.f; if (s0 + 2 > t) a2 = 0.f; if (s0 + 3 > t) a3 = 0.f;
;               u32x2 ow; ow.x = pk2(a0, a1); ow.y = pk2(a2, a3);
;               *(LAS u32x2*)(Abuf + t * KS + s0 * 2) = ow; } }
;         __syncthreads();
;         f32x4 o[4];
;         { bf16x8 af[2][4]; u32x2 q0[4][4], q1[4][4];
; #pragma unroll
;           for (int ks = 0; ks < 2; ++ks)
; #pragma unroll
;               for (int tt = 0; tt < 4; ++tt) af[ks][tt] = *(const LAS bf16x8*)(Abuf + (16 * tt + fr) * KS + ks * 64 + fq * 16);
; #pragma unroll
;           for (int ks = 0; ks < 4; ++ks)
; #pragma unroll
;               for (int tt = 0; tt < 4; ++tt) { q0[ks][tt] = *(const LAS u32x2*)(qb + (16 * tt + fr) * QS + (((4 * ks + (fq >> 1)) ^ fr) * 16) + 8 * (fq & 1)); q1[ks][tt] = *(const LAS u32x2*)(qb + (16 * tt + fr) * QS + (((4 * ks + 2 + (fq >> 1)) ^ fr) * 16) + 8 * (fq & 1)); }
;           bf16x8 sa[4];
; #pragma unroll
;           for (int ks = 0; ks < 4; ++ks) { u32x4 pw; pw.x = pk2(S[2 * ks][0], S[2 * ks][1]); pw.y = pk2(S[2 * ks][2], S[2 * ks][3]); pw.z = pk2(S[2 * ks + 1][0], S[2 * ks + 1][1]); pw.w = pk2(S[2 * ks + 1][2], S[2 * ks + 1][3]); sa[ks] = __builtin_bit_cast(bf16x8, pw); }
.LBB0_582:
	s_mul_i32 s23, s22, 0xc000
	s_add_i32 s23, s23, 0
	v_add_u32_e32 v186, s23, v90
	v_add_u32_e32 v117, s23, v89
	v_add_u32_e32 v126, s28, v186
	v_add_u32_e32 v58, v117, v91
	v_add_u32_e32 v62, v126, v91
	v_add_u32_e32 v66, v117, v92
	v_add_u32_e32 v70, v126, v92
	v_add_u32_e32 v118, v117, v93
	v_add_u32_e32 v122, v126, v93
	v_add_u32_e32 v117, v117, v94
	v_add_u32_e32 v142, v126, v94
	ds_read_b128 v[58:61], v58 offset:16384
	ds_read_b128 v[62:65], v62
	ds_read_b128 v[66:69], v66 offset:16384
	ds_read_b128 v[70:73], v70
	ds_read_b128 v[118:121], v118 offset:16384
	ds_read_b128 v[122:125], v122
	ds_read_b128 v[126:129], v117 offset:16384
	ds_read_b128 v[142:145], v142
	v_add_u32_e32 v117, s29, v186
	v_add_u32_e32 v146, v117, v91
	v_add_u32_e32 v150, v117, v92
	v_add_u32_e32 v154, v117, v93
	ds_read_b128 v[146:149], v146
	ds_read_b128 v[150:153], v150
	v_add_u32_e32 v117, v117, v94
	ds_read_b128 v[154:157], v154
	ds_read_b128 v[158:161], v117
	s_waitcnt lgkmcnt(10)
	v_mfma_f32_16x16x32_bf16 v[62:65], v[58:61], v[62:65], 0
	v_add3_u32 v117, v186, v105, v88
	v_add3_u32 v174, v186, v104, v88
	v_add3_u32 v187, v186, v107, v88
	s_waitcnt lgkmcnt(3)
	v_mfma_f32_16x16x32_bf16 v[58:61], v[58:61], v[146:149], 0
	v_cvt_pk_bf16_f32 v228, v54, v55
	v_cvt_pk_bf16_f32 v229, v56, v57
	v_cvt_pk_bf16_f32 v230, v50, v51
	v_mfma_f32_16x16x32_bf16 v[62:65], v[66:69], v[70:73], v[62:65]
	v_cvt_pk_bf16_f32 v231, v52, v53
	v_cvt_pk_bf16_f32 v232, v46, v47
	v_cvt_pk_bf16_f32 v233, v48, v49
	s_waitcnt lgkmcnt(2)
	v_mfma_f32_16x16x32_bf16 v[58:61], v[66:69], v[150:153], v[58:61]
	v_cvt_pk_bf16_f32 v234, v42, v43
	v_cvt_pk_bf16_f32 v235, v44, v45
	v_cvt_pk_bf16_f32 v236, v38, v39
	v_mfma_f32_16x16x32_bf16 v[62:65], v[118:121], v[122:125], v[62:65]
	v_cvt_pk_bf16_f32 v237, v40, v41
	v_cvt_pk_bf16_f32 v238, v34, v35
	v_cvt_pk_bf16_f32 v239, v36, v37
	s_waitcnt lgkmcnt(1)
	v_mfma_f32_16x16x32_bf16 v[58:61], v[118:121], v[154:157], v[58:61]
	v_cvt_pk_bf16_f32 v240, v30, v31
	v_cvt_pk_bf16_f32 v241, v32, v33
	v_cvt_pk_bf16_f32 v242, v26, v27
	v_mfma_f32_16x16x32_bf16 v[62:65], v[126:129], v[142:145], v[62:65]
	v_cvt_pk_bf16_f32 v243, v28, v29
	s_waitcnt lgkmcnt(0)
	v_mfma_f32_16x16x32_bf16 v[58:61], v[126:129], v[158:161], v[58:61]
	v_add3_u32 v158, v186, v103, v88
	s_nop 4
	v_cndmask_b32_e64 v62, v62, 0, s[42:43]
	v_cndmask_b32_e64 v63, 0, v63, s[44:45]
	v_cndmask_b32_e64 v64, v64, 0, s[46:47]
	v_cndmask_b32_e64 v65, v65, 0, s[48:49]
	v_cndmask_b32_e64 v58, v58, 0, s[50:51]
	v_cndmask_b32_e64 v59, 0, v59, s[52:53]
	v_cndmask_b32_e64 v60, v60, 0, s[54:55]
	v_cndmask_b32_e64 v61, v61, 0, s[56:57]
	v_cvt_pk_bf16_f32 v62, v62, v63
	v_cvt_pk_bf16_f32 v63, v64, v65
	v_cvt_pk_bf16_f32 v58, v58, v59
	v_cvt_pk_bf16_f32 v59, v60, v61
	ds_write_b64 v113, v[62:63]
	ds_write_b64 v112, v[58:59]
	s_waitcnt lgkmcnt(0)
	s_barrier
	ds_read_b128 v[58:61], v0
	ds_read_b128 v[62:65], v0 offset:64
	ds_read_b128 v[66:69], v0 offset:2304
	ds_read_b128 v[70:73], v0 offset:2368
	ds_read_b128 v[118:121], v0 offset:4608
	ds_read_b128 v[122:125], v0 offset:4672
	ds_read_b128 v[126:129], v0 offset:6912
	ds_read_b128 v[142:145], v0 offset:6976
	ds_read2st64_b64 v[146:149], v117 offset1:8
	ds_read2st64_b64 v[150:153], v158 offset1:8
	ds_read2st64_b64 v[154:157], v117 offset0:16 offset1:24
	ds_read2st64_b64 v[158:161], v158 offset0:16 offset1:24
	v_add3_u32 v117, v186, v106, v88
	ds_read2st64_b64 v[162:165], v117 offset1:8
	ds_read2st64_b64 v[166:169], v174 offset1:8
	ds_read2st64_b64 v[170:173], v117 offset0:16 offset1:24
	ds_read2st64_b64 v[174:177], v174 offset0:16 offset1:24
	v_add3_u32 v117, v186, v109, v88
	ds_read2st64_b64 v[178:181], v117 offset1:8
	ds_read2st64_b64 v[182:185], v187 offset1:8
	ds_read2st64_b64 v[204:207], v117 offset0:16 offset1:24
	ds_read2st64_b64 v[208:211], v187 offset0:16 offset1:24
	v_add3_u32 v117, v186, v110, v88
	v_add3_u32 v186, v186, v108, v88
	ds_read2st64_b64 v[212:215], v117 offset1:8
	ds_read2st64_b64 v[216:219], v186 offset1:8
	ds_read2st64_b64 v[220:223], v117 offset0:16 offset1:24
	ds_read2st64_b64 v[224:227], v186 offset0:16 offset1:24
	s_waitcnt lgkmcnt(14)
	v_mfma_f32_16x16x32_bf16 v[58:61], v[22:25], v[58:61], 0
	v_mfma_f32_16x16x32_bf16 v[66:69], v[22:25], v[66:69], 0
	v_mfma_f32_16x16x32_bf16 v[118:121], v[22:25], v[118:121], 0
	v_mfma_f32_16x16x32_bf16 v[126:129], v[22:25], v[126:129], 0
	v_mfma_f32_16x16x32_bf16 v[58:61], v[18:21], v[62:65], v[58:61]
	v_mfma_f32_16x16x32_bf16 v[62:65], v[18:21], v[70:73], v[66:69]
	v_mfma_f32_16x16x32_bf16 v[66:69], v[18:21], v[122:125], v[118:121]
	v_mfma_f32_16x16x32_bf16 v[70:73], v[18:21], v[142:145], v[126:129]
	s_nop 2
	v_mov_b32_e32 v118, v146
	v_mov_b32_e32 v119, v147
	v_mov_b32_e32 v120, v150
	v_mov_b32_e32 v121, v151
	v_mov_b32_e32 v150, v148
	v_mov_b32_e32 v151, v149
	v_mfma_f32_16x16x32_bf16 v[58:61], v[228:231], v[118:121], v[58:61]
	s_waitcnt lgkmcnt(13)
	v_mov_b32_e32 v118, v154
	v_mov_b32_e32 v119, v155
	s_waitcnt lgkmcnt(12)
	v_mov_b32_e32 v120, v158
	v_mov_b32_e32 v121, v159
	v_mov_b32_e32 v158, v156
	v_mov_b32_e32 v159, v157
	v_mfma_f32_16x16x32_bf16 v[62:65], v[228:231], v[150:153], v[62:65]
	v_mfma_f32_16x16x32_bf16 v[66:69], v[228:231], v[118:121], v[66:69]
	s_waitcnt lgkmcnt(11)
	v_mov_b32_e32 v118, v162
	v_mov_b32_e32 v119, v163
	s_waitcnt lgkmcnt(10)
; #define LAS __attribute__((address_space(3)))
; #define MFMA16(a, b, c) __builtin_amdgcn_mfma_f32_16x16x32_bf16((a), (b), (c), 0, 0, 0)
; __device__ __forceinline__ void gla_prompt_unit(const Ctx& P, int l, int b, int h, int eh, LAS unsigned char* lds) {
;     ...
;           for (int ks = 0; ks < 2; ++ks)
; #pragma unroll
;               for (int tt = 0; tt < 4; ++tt) o[tt] = MFMA16(vt[ks], af[ks][tt], o[tt]);
; #pragma unroll
;           for (int ks = 0; ks < 4; ++ks)
; #pragma unroll
;               for (int tt = 0; tt < 4; ++tt) { u32x4 qw; qw.x = q0[ks][tt].x; qw.y = q0[ks][tt].y; qw.z = q1[ks][tt].x; qw.w = q1[ks][tt].y;
;                   o[tt] = MFMA16(sa[ks], __builtin_bit_cast(bf16x8, qw), o[tt]); } }
;         __builtin_amdgcn_sched_barrier(0);
;         { const LAS float* dp = DECL + bufc * 128; bf16x8 kf[8][2]; f32x4 dv[8];
; #pragma unroll
;           for (int dt = 0; dt < 8; ++dt) { dv[dt] = *(const LAS f32x4*)(dp + 16 * dt + fq * 4);
; #pragma unroll
;               for (int ks = 0; ks < 2; ++ks) kf[dt][ks] = *(const LAS bf16x8*)(eb + (16 * dt + fr) * ES + (((ks * 4 + fq) ^ (fr & 7)) * 16)); }
;           __builtin_amdgcn_sched_barrier(0);
; #pragma unroll
;           for (int dt = 0; dt < 8; ++dt) S[dt] = S[dt] * dv[dt];
; #pragma unroll
;           for (int ks = 0; ks < 2; ++ks)
; #pragma unroll
;               for (int dt = 0; dt < 8; ++dt) S[dt] = MFMA16(kf[dt][ks], vt[ks], S[dt]); }
;         __builtin_amdgcn_sched_barrier(0);
;         if (grp == ((c + 1) & 1)) asm volatile("s_waitcnt vmcnt(0)" ::: "memory");
	v_mov_b32_e32 v120, v166
	v_mfma_f32_16x16x32_bf16 v[70:73], v[228:231], v[158:161], v[70:73]
	v_mov_b32_e32 v121, v167
	v_mov_b32_e32 v166, v164
	v_mov_b32_e32 v167, v165
	v_mfma_f32_16x16x32_bf16 v[58:61], v[232:235], v[118:121], v[58:61]
	s_waitcnt lgkmcnt(9)
	v_mov_b32_e32 v118, v170
	v_mov_b32_e32 v119, v171
	s_waitcnt lgkmcnt(8)
	v_mov_b32_e32 v120, v174
	v_mov_b32_e32 v121, v175
	v_mov_b32_e32 v174, v172
	v_mov_b32_e32 v175, v173
	v_mfma_f32_16x16x32_bf16 v[62:65], v[232:235], v[166:169], v[62:65]
	v_mfma_f32_16x16x32_bf16 v[66:69], v[232:235], v[118:121], v[66:69]
	s_waitcnt lgkmcnt(7)
	v_mov_b32_e32 v118, v178
	v_mov_b32_e32 v119, v179
	s_waitcnt lgkmcnt(6)
	v_mov_b32_e32 v120, v182
	v_mfma_f32_16x16x32_bf16 v[70:73], v[232:235], v[174:177], v[70:73]
	v_mov_b32_e32 v121, v183
	v_mov_b32_e32 v182, v180
	v_mov_b32_e32 v183, v181
	v_mfma_f32_16x16x32_bf16 v[58:61], v[236:239], v[118:121], v[58:61]
	s_waitcnt lgkmcnt(5)
	v_mov_b32_e32 v118, v204
	v_mov_b32_e32 v119, v205
	s_waitcnt lgkmcnt(4)
	v_mov_b32_e32 v120, v208
	v_mov_b32_e32 v121, v209
	v_mov_b32_e32 v208, v206
	v_mov_b32_e32 v209, v207
	v_mfma_f32_16x16x32_bf16 v[62:65], v[236:239], v[182:185], v[62:65]
	v_mfma_f32_16x16x32_bf16 v[118:121], v[236:239], v[118:121], v[66:69]
	v_mfma_f32_16x16x32_bf16 v[122:125], v[236:239], v[208:211], v[70:73]
	s_waitcnt lgkmcnt(3)
	s_nop 0
	v_mov_b32_e32 v66, v212
	v_mov_b32_e32 v67, v213
	s_waitcnt lgkmcnt(2)
	v_mov_b32_e32 v68, v216
	v_mov_b32_e32 v69, v217
	v_mov_b32_e32 v216, v214
	v_mov_b32_e32 v217, v215
	v_mfma_f32_16x16x32_bf16 v[70:73], v[240:243], v[66:69], v[58:61]
	s_waitcnt lgkmcnt(1)
	s_nop 1
	v_mov_b32_e32 v58, v220
	v_mov_b32_e32 v59, v221
	s_waitcnt lgkmcnt(0)
	v_mov_b32_e32 v60, v224
	v_mov_b32_e32 v61, v225
	v_mov_b32_e32 v224, v222
	v_mov_b32_e32 v225, v223
	v_mfma_f32_16x16x32_bf16 v[66:69], v[240:243], v[216:219], v[62:65]
	v_mfma_f32_16x16x32_bf16 v[62:65], v[240:243], v[58:61], v[118:121]
	v_mfma_f32_16x16x32_bf16 v[58:61], v[240:243], v[224:227], v[122:125]
	v_add_u32_e32 v126, s23, v100
	v_add_u32_e32 v146, s23, v101
	v_add_u32_e32 v162, s23, v102
	v_lshl_add_u32 v117, s22, 9, v85
	v_add_u32_e32 v118, s23, v99
	v_add_u32_e32 v127, v126, v97
	v_add_u32_e32 v142, v126, v98
	v_add_u32_e32 v147, v146, v97
	v_add_u32_e32 v150, v146, v98
	v_add_u32_e32 v163, v162, v97
	v_add_u32_e32 v166, v162, v98
	v_add_u32_e32 v186, v118, v97
	v_add_u32_e32 v187, v118, v98
	ds_read_b128 v[118:121], v117
	ds_read_b128 v[122:125], v117 offset:64
	ds_read_b128 v[126:129], v127 offset:32768
	ds_read_b128 v[142:145], v142 offset:32768
	ds_read_b128 v[146:149], v147 offset:32768
	ds_read_b128 v[150:153], v150 offset:32768
	ds_read_b128 v[154:157], v117 offset:128
	ds_read_b128 v[158:161], v117 offset:192
	ds_read_b128 v[162:165], v163 offset:32768
	ds_read_b128 v[166:169], v166 offset:32768
	ds_read_b128 v[170:173], v186 offset:32768
	ds_read_b128 v[174:177], v186 offset:40960
	ds_read_b128 v[178:181], v117 offset:256
	ds_read_b128 v[182:185], v117 offset:320
	ds_read_b128 v[204:207], v187 offset:40960
	ds_read_b128 v[208:211], v187 offset:43008
	ds_read_b128 v[212:215], v186 offset:43008
	ds_read_b128 v[216:219], v186 offset:45056
	ds_read_b128 v[220:223], v117 offset:384
	ds_read_b128 v[224:227], v117 offset:448
	ds_read_b128 v[228:231], v187 offset:32768
	ds_read_b128 v[232:235], v186 offset:47104
	ds_read_b128 v[236:239], v187 offset:45056
	ds_read_b128 v[240:243], v187 offset:47104
	s_waitcnt lgkmcnt(14)
	v_pk_mul_f32 v[56:57], v[56:57], v[120:121]
	v_pk_mul_f32 v[54:55], v[54:55], v[118:119]
	v_pk_mul_f32 v[52:53], v[52:53], v[124:125]
	v_pk_mul_f32 v[50:51], v[50:51], v[122:123]
	v_pk_mul_f32 v[48:49], v[48:49], v[156:157]
	v_pk_mul_f32 v[46:47], v[46:47], v[154:155]
	v_pk_mul_f32 v[44:45], v[44:45], v[160:161]
	v_pk_mul_f32 v[42:43], v[42:43], v[158:159]
	s_waitcnt lgkmcnt(11)
	v_pk_mul_f32 v[40:41], v[40:41], v[180:181]
	v_pk_mul_f32 v[38:39], v[38:39], v[178:179]
	s_waitcnt lgkmcnt(10)
	v_pk_mul_f32 v[36:37], v[36:37], v[184:185]
	v_pk_mul_f32 v[34:35], v[34:35], v[182:183]
	s_waitcnt lgkmcnt(5)
	v_pk_mul_f32 v[32:33], v[32:33], v[222:223]
	v_pk_mul_f32 v[30:31], v[30:31], v[220:221]
	s_waitcnt lgkmcnt(4)
	v_pk_mul_f32 v[28:29], v[28:29], v[226:227]
	v_pk_mul_f32 v[26:27], v[26:27], v[224:225]
	v_mfma_f32_16x16x32_bf16 v[54:57], v[170:173], v[22:25], v[54:57]
	v_mfma_f32_16x16x32_bf16 v[50:53], v[126:129], v[22:25], v[50:53]
	v_mfma_f32_16x16x32_bf16 v[46:49], v[146:149], v[22:25], v[46:49]
	v_mfma_f32_16x16x32_bf16 v[42:45], v[162:165], v[22:25], v[42:45]
	v_mfma_f32_16x16x32_bf16 v[38:41], v[174:177], v[22:25], v[38:41]
	v_mfma_f32_16x16x32_bf16 v[34:37], v[212:215], v[22:25], v[34:37]
	v_mfma_f32_16x16x32_bf16 v[30:33], v[216:219], v[22:25], v[30:33]
	s_waitcnt lgkmcnt(2)
	v_mfma_f32_16x16x32_bf16 v[22:25], v[232:235], v[22:25], v[26:29]
	v_mfma_f32_16x16x32_bf16 v[54:57], v[228:231], v[18:21], v[54:57]
	v_mfma_f32_16x16x32_bf16 v[50:53], v[142:145], v[18:21], v[50:53]
	v_mfma_f32_16x16x32_bf16 v[46:49], v[150:153], v[18:21], v[46:49]
	v_mfma_f32_16x16x32_bf16 v[42:45], v[166:169], v[18:21], v[42:45]
	v_mfma_f32_16x16x32_bf16 v[38:41], v[204:207], v[18:21], v[38:41]
	v_mfma_f32_16x16x32_bf16 v[34:37], v[208:211], v[18:21], v[34:37]
	s_waitcnt lgkmcnt(1)
	v_mfma_f32_16x16x32_bf16 v[30:33], v[236:239], v[18:21], v[30:33]
	s_waitcnt lgkmcnt(0)
	v_mfma_f32_16x16x32_bf16 v[26:29], v[240:243], v[18:21], v[22:25]
	s_and_b32 s22, s61, 1
	s_cmp_lg_u32 s35, s22
	s_cbranch_scc1 .LBB0_584
	s_waitcnt vmcnt(0)
